# up K-loop: last iteration split into a tail copy without the 14 wasted re-reads; vmcnt(0) before w_in/w_out K-loops removed
# speedup vs baseline: 1.0067x; 1.0007x over previous
.LBB0_160:
	s_add_u32 s44, s76, s38
	s_addc_u32 s45, s77, s39
	s_add_u32 s44, s44, 0x3800900
	s_addc_u32 s45, s45, 0
	s_add_u32 s85, s78, s38
	s_addc_u32 s93, s79, s39
	s_add_i32 vcc_lo, 0, 0x10000
	s_cmpk_eq_i32 s38, 0x700
	s_cselect_b32 s59, s29, s45
	s_cselect_b32 s58, s28, s44
	s_cselect_b32 s45, s7, s93
	s_cselect_b32 s44, s6, s85
	s_add_i32 s85, 0, 0x14000
	v_add_u32_e32 v154, vcc_lo, v140
	v_add_u32_e32 v170, s85, v140
	ds_read_b128 v[142:145], v154
	ds_read_b128 v[146:149], v154 offset:1024
	ds_read_b128 v[150:153], v154 offset:2048
	ds_read_b128 v[154:157], v154 offset:3072
	ds_read_b128 v[158:161], v170
	ds_read_b128 v[162:165], v170 offset:1024
	ds_read_b128 v[166:169], v170 offset:2048
	ds_read_b128 v[170:173], v170 offset:3072
	v_lshl_add_u64 v[208:209], v[136:137], 0, s[38:39]
	s_add_i32 m0, s9, 0xc000
	ds_read_b128 v[174:177], v141
	ds_read_b128 v[178:181], v141 offset:1024
	ds_read_b128 v[182:185], v141 offset:2048
	ds_read_b128 v[186:189], v141 offset:3072
	ds_read_b128 v[192:195], v141 offset:4096
	ds_read_b128 v[196:199], v141 offset:5120
	ds_read_b128 v[200:203], v141 offset:6144
	ds_read_b128 v[204:207], v141 offset:7168
	global_load_lds_dwordx4 v[208:209], off
	v_lshl_add_u64 v[208:209], v[138:139], 0, s[38:39]
	s_add_i32 m0, s9, 0xe000
	s_nop 0
	global_load_lds_dwordx4 v[208:209], off
	s_waitcnt vmcnt(8)
	s_waitcnt lgkmcnt(0)
	s_barrier
	s_setprio 1
	s_waitcnt lgkmcnt(0)
	v_mfma_f32_16x16x32_bf16 v[126:129], v[142:145], v[174:177], v[126:129]
	v_mfma_f32_16x16x32_bf16 v[122:125], v[150:153], v[174:177], v[122:125]
	v_mfma_f32_16x16x32_bf16 v[118:121], v[142:145], v[182:185], v[118:121]
	v_mfma_f32_16x16x32_bf16 v[114:117], v[150:153], v[182:185], v[114:117]
	v_mfma_f32_16x16x32_bf16 v[102:105], v[142:145], v[192:195], v[102:105]
	v_mfma_f32_16x16x32_bf16 v[98:101], v[150:153], v[192:195], v[98:101]
	v_mfma_f32_16x16x32_bf16 v[86:89], v[142:145], v[200:203], v[86:89]
	v_mfma_f32_16x16x32_bf16 v[82:85], v[150:153], v[200:203], v[82:85]
	v_mfma_f32_16x16x32_bf16 v[126:129], v[146:149], v[178:181], v[126:129]
	v_mfma_f32_16x16x32_bf16 v[122:125], v[154:157], v[178:181], v[122:125]
	v_mfma_f32_16x16x32_bf16 v[118:121], v[146:149], v[186:189], v[118:121]
	v_mfma_f32_16x16x32_bf16 v[114:117], v[154:157], v[186:189], v[114:117]
	v_mfma_f32_16x16x32_bf16 v[102:105], v[146:149], v[196:199], v[102:105]
	v_mfma_f32_16x16x32_bf16 v[98:101], v[154:157], v[196:199], v[98:101]
	v_mfma_f32_16x16x32_bf16 v[86:89], v[146:149], v[204:207], v[86:89]
	v_mfma_f32_16x16x32_bf16 v[82:85], v[154:157], v[204:207], v[82:85]
	s_setprio 0
	s_setprio 1
	v_mfma_f32_16x16x32_bf16 v[110:113], v[158:161], v[174:177], v[110:113]
	v_mfma_f32_16x16x32_bf16 v[106:109], v[166:169], v[174:177], v[106:109]
	v_mfma_f32_16x16x32_bf16 v[94:97], v[158:161], v[182:185], v[94:97]
	v_mfma_f32_16x16x32_bf16 v[90:93], v[166:169], v[182:185], v[90:93]
	v_mfma_f32_16x16x32_bf16 v[78:81], v[158:161], v[192:195], v[78:81]
	v_mfma_f32_16x16x32_bf16 v[74:77], v[166:169], v[192:195], v[74:77]
	v_mfma_f32_16x16x32_bf16 v[70:73], v[158:161], v[200:203], v[70:73]
	v_mfma_f32_16x16x32_bf16 v[66:69], v[166:169], v[200:203], v[66:69]
	v_mfma_f32_16x16x32_bf16 v[110:113], v[162:165], v[178:181], v[110:113]
	v_mfma_f32_16x16x32_bf16 v[106:109], v[170:173], v[178:181], v[106:109]
	v_mfma_f32_16x16x32_bf16 v[94:97], v[162:165], v[186:189], v[94:97]
	v_mfma_f32_16x16x32_bf16 v[90:93], v[170:173], v[186:189], v[90:93]
	v_mfma_f32_16x16x32_bf16 v[78:81], v[162:165], v[196:199], v[78:81]
	v_mfma_f32_16x16x32_bf16 v[74:77], v[170:173], v[196:199], v[74:77]
	v_mfma_f32_16x16x32_bf16 v[70:73], v[162:165], v[204:207], v[70:73]
	v_mfma_f32_16x16x32_bf16 v[66:69], v[170:173], v[204:207], v[66:69]
	s_setprio 0
	s_barrier
	s_add_i32 s93, vcc_lo, s49
	v_lshl_add_u64 v[208:209], s[44:45], 0, v[0:1]
	s_mov_b32 m0, s93
	ds_read_b128 v[174:177], v141 offset:16384
	ds_read_b128 v[178:181], v141 offset:17408
	ds_read_b128 v[182:185], v141 offset:18432
	ds_read_b128 v[186:189], v141 offset:19456
	ds_read_b128 v[192:195], v141 offset:20480
	ds_read_b128 v[196:199], v141 offset:21504
	ds_read_b128 v[200:203], v141 offset:22528
	ds_read_b128 v[204:207], v141 offset:23552
	global_load_lds_dwordx4 v[208:209], off
	s_add_i32 m0, s93, 0x2000
	s_add_u32 vcc_lo, s44, 0x40000
	v_lshl_add_u64 v[210:211], s[44:45], 0, v[134:135]
	s_addc_u32 vcc_hi, s45, 0
	s_add_i32 s85, s85, s49
	global_load_lds_dwordx4 v[210:211], off
	v_lshl_add_u64 v[212:213], vcc, 0, v[0:1]
	s_mov_b32 m0, s85
	v_lshl_add_u64 v[214:215], s[58:59], 0, v[132:133]
	global_load_lds_dwordx4 v[212:213], off
	v_lshl_add_u64 v[212:213], vcc, 0, v[134:135]
	s_add_i32 m0, s85, 0x2000
	s_nop 0
	global_load_lds_dwordx4 v[212:213], off
	v_lshl_add_u64 v[212:213], s[58:59], 0, v[130:131]
	s_mov_b32 m0, s9
	s_nop 0
	global_load_lds_dwordx4 v[212:213], off
	s_mov_b32 m0, s56
	s_nop 0
	global_load_lds_dwordx4 v[214:215], off
	s_waitcnt vmcnt(8)
	s_waitcnt lgkmcnt(0)
	s_barrier
	s_setprio 1
	s_waitcnt lgkmcnt(0)
	v_mfma_f32_16x16x32_bf16 v[62:65], v[142:145], v[174:177], v[62:65]
	v_mfma_f32_16x16x32_bf16 v[58:61], v[150:153], v[174:177], v[58:61]
	v_mfma_f32_16x16x32_bf16 v[54:57], v[142:145], v[182:185], v[54:57]
	v_mfma_f32_16x16x32_bf16 v[50:53], v[150:153], v[182:185], v[50:53]
	v_mfma_f32_16x16x32_bf16 v[38:41], v[142:145], v[192:195], v[38:41]
	v_mfma_f32_16x16x32_bf16 v[34:37], v[150:153], v[192:195], v[34:37]
	v_mfma_f32_16x16x32_bf16 v[22:25], v[142:145], v[200:203], v[22:25]
	v_mfma_f32_16x16x32_bf16 v[18:21], v[150:153], v[200:203], v[18:21]
	v_mfma_f32_16x16x32_bf16 v[62:65], v[146:149], v[178:181], v[62:65]
	v_mfma_f32_16x16x32_bf16 v[58:61], v[154:157], v[178:181], v[58:61]
	v_mfma_f32_16x16x32_bf16 v[54:57], v[146:149], v[186:189], v[54:57]
	v_mfma_f32_16x16x32_bf16 v[50:53], v[154:157], v[186:189], v[50:53]
	v_mfma_f32_16x16x32_bf16 v[38:41], v[146:149], v[196:199], v[38:41]
	v_mfma_f32_16x16x32_bf16 v[34:37], v[154:157], v[196:199], v[34:37]
	v_mfma_f32_16x16x32_bf16 v[22:25], v[146:149], v[204:207], v[22:25]
	v_mfma_f32_16x16x32_bf16 v[18:21], v[154:157], v[204:207], v[18:21]
	s_setprio 0
	s_setprio 1
	v_mfma_f32_16x16x32_bf16 v[46:49], v[158:161], v[174:177], v[46:49]
	v_mfma_f32_16x16x32_bf16 v[42:45], v[166:169], v[174:177], v[42:45]
	v_mfma_f32_16x16x32_bf16 v[30:33], v[158:161], v[182:185], v[30:33]
	v_mfma_f32_16x16x32_bf16 v[26:29], v[166:169], v[182:185], v[26:29]
	v_mfma_f32_16x16x32_bf16 v[14:17], v[158:161], v[192:195], v[14:17]
	v_mfma_f32_16x16x32_bf16 v[10:13], v[166:169], v[192:195], v[10:13]
	v_mfma_f32_16x16x32_bf16 v[6:9], v[158:161], v[200:203], v[6:9]
	v_mfma_f32_16x16x32_bf16 v[2:5], v[166:169], v[200:203], v[2:5]
	v_mfma_f32_16x16x32_bf16 v[46:49], v[162:165], v[178:181], v[46:49]
	v_mfma_f32_16x16x32_bf16 v[42:45], v[170:173], v[178:181], v[42:45]
	v_mfma_f32_16x16x32_bf16 v[30:33], v[162:165], v[186:189], v[30:33]
	v_mfma_f32_16x16x32_bf16 v[26:29], v[170:173], v[186:189], v[26:29]
	v_mfma_f32_16x16x32_bf16 v[14:17], v[162:165], v[196:199], v[14:17]
	v_mfma_f32_16x16x32_bf16 v[10:13], v[170:173], v[196:199], v[10:13]
	v_mfma_f32_16x16x32_bf16 v[6:9], v[162:165], v[204:207], v[6:9]
	v_mfma_f32_16x16x32_bf16 v[2:5], v[170:173], v[204:207], v[2:5]
	s_setprio 0
	s_barrier
	s_add_i32 s85, 0, 0x18000
	s_add_i32 s93, 0, 0x1c000
	v_add_u32_e32 v154, s85, v140
	v_add_u32_e32 v170, s93, v140
	ds_read_b128 v[142:145], v154
	ds_read_b128 v[146:149], v154 offset:1024
	ds_read_b128 v[150:153], v154 offset:2048
	ds_read_b128 v[154:157], v154 offset:3072
	ds_read_b128 v[158:161], v170
	ds_read_b128 v[162:165], v170 offset:1024
	ds_read_b128 v[166:169], v170 offset:2048
	ds_read_b128 v[170:173], v170 offset:3072
	s_add_u32 s58, s58, 0x40000
	s_addc_u32 s59, s59, 0
	s_mov_b32 m0, s57
	v_lshl_add_u64 v[216:217], s[58:59], 0, v[130:131]
	ds_read_b128 v[174:177], v141 offset:32768
	ds_read_b128 v[178:181], v141 offset:33792
	ds_read_b128 v[182:185], v141 offset:34816
	ds_read_b128 v[186:189], v141 offset:35840
	ds_read_b128 v[192:195], v141 offset:36864
	ds_read_b128 v[196:199], v141 offset:37888
	ds_read_b128 v[200:203], v141 offset:38912
	ds_read_b128 v[204:207], v141 offset:39936
	global_load_lds_dwordx4 v[216:217], off
	v_lshl_add_u64 v[216:217], s[58:59], 0, v[132:133]
	s_mov_b32 m0, s66
	s_nop 0
	global_load_lds_dwordx4 v[216:217], off
	s_waitcnt vmcnt(8)
	s_waitcnt lgkmcnt(0)
	s_barrier
	s_setprio 1
	s_waitcnt lgkmcnt(0)
	v_mfma_f32_16x16x32_bf16 v[126:129], v[142:145], v[174:177], v[126:129]
	v_mfma_f32_16x16x32_bf16 v[122:125], v[150:153], v[174:177], v[122:125]
	v_mfma_f32_16x16x32_bf16 v[118:121], v[142:145], v[182:185], v[118:121]
	v_mfma_f32_16x16x32_bf16 v[114:117], v[150:153], v[182:185], v[114:117]
	v_mfma_f32_16x16x32_bf16 v[102:105], v[142:145], v[192:195], v[102:105]
	v_mfma_f32_16x16x32_bf16 v[98:101], v[150:153], v[192:195], v[98:101]
	v_mfma_f32_16x16x32_bf16 v[86:89], v[142:145], v[200:203], v[86:89]
	v_mfma_f32_16x16x32_bf16 v[82:85], v[150:153], v[200:203], v[82:85]
	v_mfma_f32_16x16x32_bf16 v[126:129], v[146:149], v[178:181], v[126:129]
	v_mfma_f32_16x16x32_bf16 v[122:125], v[154:157], v[178:181], v[122:125]
	v_mfma_f32_16x16x32_bf16 v[118:121], v[146:149], v[186:189], v[118:121]
	v_mfma_f32_16x16x32_bf16 v[114:117], v[154:157], v[186:189], v[114:117]
	v_mfma_f32_16x16x32_bf16 v[102:105], v[146:149], v[196:199], v[102:105]
	v_mfma_f32_16x16x32_bf16 v[98:101], v[154:157], v[196:199], v[98:101]
	v_mfma_f32_16x16x32_bf16 v[86:89], v[146:149], v[204:207], v[86:89]
	v_mfma_f32_16x16x32_bf16 v[82:85], v[154:157], v[204:207], v[82:85]
	s_setprio 0
	s_setprio 1
	v_mfma_f32_16x16x32_bf16 v[110:113], v[158:161], v[174:177], v[110:113]
	v_mfma_f32_16x16x32_bf16 v[106:109], v[166:169], v[174:177], v[106:109]
	v_mfma_f32_16x16x32_bf16 v[94:97], v[158:161], v[182:185], v[94:97]
	v_mfma_f32_16x16x32_bf16 v[90:93], v[166:169], v[182:185], v[90:93]
	v_mfma_f32_16x16x32_bf16 v[78:81], v[158:161], v[192:195], v[78:81]
	v_mfma_f32_16x16x32_bf16 v[74:77], v[166:169], v[192:195], v[74:77]
	v_mfma_f32_16x16x32_bf16 v[70:73], v[158:161], v[200:203], v[70:73]
	v_mfma_f32_16x16x32_bf16 v[66:69], v[166:169], v[200:203], v[66:69]
	v_mfma_f32_16x16x32_bf16 v[110:113], v[162:165], v[178:181], v[110:113]
	v_mfma_f32_16x16x32_bf16 v[106:109], v[170:173], v[178:181], v[106:109]
	v_mfma_f32_16x16x32_bf16 v[94:97], v[162:165], v[186:189], v[94:97]
	v_mfma_f32_16x16x32_bf16 v[90:93], v[170:173], v[186:189], v[90:93]
	v_mfma_f32_16x16x32_bf16 v[78:81], v[162:165], v[196:199], v[78:81]
	v_mfma_f32_16x16x32_bf16 v[74:77], v[170:173], v[196:199], v[74:77]
	v_mfma_f32_16x16x32_bf16 v[70:73], v[162:165], v[204:207], v[70:73]
	v_mfma_f32_16x16x32_bf16 v[66:69], v[170:173], v[204:207], v[66:69]
	s_setprio 0
	s_barrier
	s_add_i32 s58, s85, s49
	v_lshl_add_u64 v[208:209], v[208:209], 0, s[86:87]
	s_mov_b32 m0, s58
	ds_read_b128 v[174:177], v141 offset:49152
	ds_read_b128 v[178:181], v141 offset:50176
	ds_read_b128 v[182:185], v141 offset:51200
	ds_read_b128 v[186:189], v141 offset:52224
	ds_read_b128 v[192:195], v141 offset:53248
	ds_read_b128 v[196:199], v141 offset:54272
	ds_read_b128 v[200:203], v141 offset:55296
	ds_read_b128 v[204:207], v141 offset:56320
	global_load_lds_dwordx4 v[208:209], off
	s_add_i32 m0, s58, 0x2000
	s_add_u32 s44, s44, 0x40080
	v_lshl_add_u64 v[208:209], v[210:211], 0, s[86:87]
	s_addc_u32 s45, s45, 0
	s_add_i32 s58, s93, s49
	global_load_lds_dwordx4 v[208:209], off
	v_lshl_add_u64 v[208:209], s[44:45], 0, v[0:1]
	s_mov_b32 m0, s58
	s_nop 0
	global_load_lds_dwordx4 v[208:209], off
	v_lshl_add_u64 v[208:209], s[44:45], 0, v[134:135]
	s_add_i32 m0, s58, 0x2000
	s_nop 0
	global_load_lds_dwordx4 v[208:209], off
	v_lshl_add_u64 v[208:209], v[212:213], 0, s[86:87]
	s_mov_b32 m0, s71
	s_nop 0
	global_load_lds_dwordx4 v[208:209], off
	v_lshl_add_u64 v[208:209], v[214:215], 0, s[86:87]
	s_mov_b32 m0, s74
	s_nop 0
	global_load_lds_dwordx4 v[208:209], off
	s_waitcnt vmcnt(8)
	s_waitcnt lgkmcnt(0)
	s_barrier
	s_setprio 1
	s_waitcnt lgkmcnt(0)
	v_mfma_f32_16x16x32_bf16 v[62:65], v[142:145], v[174:177], v[62:65]
	v_mfma_f32_16x16x32_bf16 v[58:61], v[150:153], v[174:177], v[58:61]
	v_mfma_f32_16x16x32_bf16 v[54:57], v[142:145], v[182:185], v[54:57]
	v_mfma_f32_16x16x32_bf16 v[50:53], v[150:153], v[182:185], v[50:53]
	v_mfma_f32_16x16x32_bf16 v[38:41], v[142:145], v[192:195], v[38:41]
	v_mfma_f32_16x16x32_bf16 v[34:37], v[150:153], v[192:195], v[34:37]
	v_mfma_f32_16x16x32_bf16 v[22:25], v[142:145], v[200:203], v[22:25]
	v_mfma_f32_16x16x32_bf16 v[18:21], v[150:153], v[200:203], v[18:21]
	v_mfma_f32_16x16x32_bf16 v[62:65], v[146:149], v[178:181], v[62:65]
	v_mfma_f32_16x16x32_bf16 v[58:61], v[154:157], v[178:181], v[58:61]
	v_mfma_f32_16x16x32_bf16 v[54:57], v[146:149], v[186:189], v[54:57]
	v_mfma_f32_16x16x32_bf16 v[50:53], v[154:157], v[186:189], v[50:53]
	v_mfma_f32_16x16x32_bf16 v[38:41], v[146:149], v[196:199], v[38:41]
	v_mfma_f32_16x16x32_bf16 v[34:37], v[154:157], v[196:199], v[34:37]
	v_mfma_f32_16x16x32_bf16 v[22:25], v[146:149], v[204:207], v[22:25]
	v_mfma_f32_16x16x32_bf16 v[18:21], v[154:157], v[204:207], v[18:21]
	s_setprio 0
	s_setprio 1
	v_mfma_f32_16x16x32_bf16 v[46:49], v[158:161], v[174:177], v[46:49]
	v_mfma_f32_16x16x32_bf16 v[42:45], v[166:169], v[174:177], v[42:45]
	v_mfma_f32_16x16x32_bf16 v[30:33], v[158:161], v[182:185], v[30:33]
	v_mfma_f32_16x16x32_bf16 v[26:29], v[166:169], v[182:185], v[26:29]
	v_mfma_f32_16x16x32_bf16 v[14:17], v[158:161], v[192:195], v[14:17]
	v_mfma_f32_16x16x32_bf16 v[10:13], v[166:169], v[192:195], v[10:13]
	v_mfma_f32_16x16x32_bf16 v[6:9], v[158:161], v[200:203], v[6:9]
	v_mfma_f32_16x16x32_bf16 v[2:5], v[166:169], v[200:203], v[2:5]
	v_mfma_f32_16x16x32_bf16 v[46:49], v[162:165], v[178:181], v[46:49]
	v_mfma_f32_16x16x32_bf16 v[42:45], v[170:173], v[178:181], v[42:45]
	v_mfma_f32_16x16x32_bf16 v[30:33], v[162:165], v[186:189], v[30:33]
	v_mfma_f32_16x16x32_bf16 v[26:29], v[170:173], v[186:189], v[26:29]
	v_mfma_f32_16x16x32_bf16 v[14:17], v[162:165], v[196:199], v[14:17]
	v_mfma_f32_16x16x32_bf16 v[10:13], v[170:173], v[196:199], v[10:13]
	v_mfma_f32_16x16x32_bf16 v[6:9], v[162:165], v[204:207], v[6:9]
	v_mfma_f32_16x16x32_bf16 v[2:5], v[170:173], v[204:207], v[2:5]
	s_setprio 0
	s_barrier
	s_add_i32 s81, s81, 2
	s_add_u32 s38, s38, 0x100
	s_addc_u32 s39, s39, 0
	s_cmp_lt_u32 s81, 12
	s_cbranch_scc1 .LBB0_160
	s_add_u32 s44, s76, s38
	s_addc_u32 s45, s77, s39
	s_add_u32 s44, s44, 0x3800900
	s_addc_u32 s45, s45, 0
	s_add_u32 s85, s78, s38
	s_addc_u32 s93, s79, s39
	s_add_i32 vcc_lo, 0, 0x10000
	s_cmpk_eq_i32 s38, 0x700
	s_cselect_b32 s59, s29, s45
	s_cselect_b32 s58, s28, s44
	s_cselect_b32 s45, s7, s93
	s_cselect_b32 s44, s6, s85
	s_add_i32 s85, 0, 0x14000
	v_add_u32_e32 v154, vcc_lo, v140
	v_add_u32_e32 v170, s85, v140
	ds_read_b128 v[142:145], v154
	ds_read_b128 v[146:149], v154 offset:1024
	ds_read_b128 v[150:153], v154 offset:2048
	ds_read_b128 v[154:157], v154 offset:3072
	ds_read_b128 v[158:161], v170
	ds_read_b128 v[162:165], v170 offset:1024
	ds_read_b128 v[166:169], v170 offset:2048
	ds_read_b128 v[170:173], v170 offset:3072
	v_lshl_add_u64 v[208:209], v[136:137], 0, s[38:39]
	s_add_i32 m0, s9, 0xc000
	ds_read_b128 v[174:177], v141
	ds_read_b128 v[178:181], v141 offset:1024
	ds_read_b128 v[182:185], v141 offset:2048
	ds_read_b128 v[186:189], v141 offset:3072
	ds_read_b128 v[192:195], v141 offset:4096
	ds_read_b128 v[196:199], v141 offset:5120
	ds_read_b128 v[200:203], v141 offset:6144
	ds_read_b128 v[204:207], v141 offset:7168
	global_load_lds_dwordx4 v[208:209], off
	v_lshl_add_u64 v[208:209], v[138:139], 0, s[38:39]
	s_add_i32 m0, s9, 0xe000
	s_nop 0
	global_load_lds_dwordx4 v[208:209], off
	s_waitcnt vmcnt(8)
	s_waitcnt lgkmcnt(0)
	s_barrier
	s_setprio 1
	s_waitcnt lgkmcnt(0)
	v_mfma_f32_16x16x32_bf16 v[126:129], v[142:145], v[174:177], v[126:129]
	v_mfma_f32_16x16x32_bf16 v[122:125], v[150:153], v[174:177], v[122:125]
	v_mfma_f32_16x16x32_bf16 v[118:121], v[142:145], v[182:185], v[118:121]
	v_mfma_f32_16x16x32_bf16 v[114:117], v[150:153], v[182:185], v[114:117]
	v_mfma_f32_16x16x32_bf16 v[102:105], v[142:145], v[192:195], v[102:105]
	v_mfma_f32_16x16x32_bf16 v[98:101], v[150:153], v[192:195], v[98:101]
	v_mfma_f32_16x16x32_bf16 v[86:89], v[142:145], v[200:203], v[86:89]
	v_mfma_f32_16x16x32_bf16 v[82:85], v[150:153], v[200:203], v[82:85]
	v_mfma_f32_16x16x32_bf16 v[126:129], v[146:149], v[178:181], v[126:129]
	v_mfma_f32_16x16x32_bf16 v[122:125], v[154:157], v[178:181], v[122:125]
	v_mfma_f32_16x16x32_bf16 v[118:121], v[146:149], v[186:189], v[118:121]
	v_mfma_f32_16x16x32_bf16 v[114:117], v[154:157], v[186:189], v[114:117]
	v_mfma_f32_16x16x32_bf16 v[102:105], v[146:149], v[196:199], v[102:105]
	v_mfma_f32_16x16x32_bf16 v[98:101], v[154:157], v[196:199], v[98:101]
	v_mfma_f32_16x16x32_bf16 v[86:89], v[146:149], v[204:207], v[86:89]
	v_mfma_f32_16x16x32_bf16 v[82:85], v[154:157], v[204:207], v[82:85]
	s_setprio 0
	s_setprio 1
	v_mfma_f32_16x16x32_bf16 v[110:113], v[158:161], v[174:177], v[110:113]
	v_mfma_f32_16x16x32_bf16 v[106:109], v[166:169], v[174:177], v[106:109]
	v_mfma_f32_16x16x32_bf16 v[94:97], v[158:161], v[182:185], v[94:97]
	v_mfma_f32_16x16x32_bf16 v[90:93], v[166:169], v[182:185], v[90:93]
	v_mfma_f32_16x16x32_bf16 v[78:81], v[158:161], v[192:195], v[78:81]
	v_mfma_f32_16x16x32_bf16 v[74:77], v[166:169], v[192:195], v[74:77]
	v_mfma_f32_16x16x32_bf16 v[70:73], v[158:161], v[200:203], v[70:73]
	v_mfma_f32_16x16x32_bf16 v[66:69], v[166:169], v[200:203], v[66:69]
	v_mfma_f32_16x16x32_bf16 v[110:113], v[162:165], v[178:181], v[110:113]
	v_mfma_f32_16x16x32_bf16 v[106:109], v[170:173], v[178:181], v[106:109]
	v_mfma_f32_16x16x32_bf16 v[94:97], v[162:165], v[186:189], v[94:97]
	v_mfma_f32_16x16x32_bf16 v[90:93], v[170:173], v[186:189], v[90:93]
	v_mfma_f32_16x16x32_bf16 v[78:81], v[162:165], v[196:199], v[78:81]
	v_mfma_f32_16x16x32_bf16 v[74:77], v[170:173], v[196:199], v[74:77]
	v_mfma_f32_16x16x32_bf16 v[70:73], v[162:165], v[204:207], v[70:73]
	v_mfma_f32_16x16x32_bf16 v[66:69], v[170:173], v[204:207], v[66:69]
	s_setprio 0
	s_barrier
	s_add_i32 s93, vcc_lo, s49
	v_lshl_add_u64 v[208:209], s[44:45], 0, v[0:1]
	s_mov_b32 m0, s93
	ds_read_b128 v[174:177], v141 offset:16384
	ds_read_b128 v[178:181], v141 offset:17408
	ds_read_b128 v[182:185], v141 offset:18432
	ds_read_b128 v[186:189], v141 offset:19456
	ds_read_b128 v[192:195], v141 offset:20480
	ds_read_b128 v[196:199], v141 offset:21504
	ds_read_b128 v[200:203], v141 offset:22528
	ds_read_b128 v[204:207], v141 offset:23552
	s_add_i32 m0, s93, 0x2000
	s_add_u32 vcc_lo, s44, 0x40000
	v_lshl_add_u64 v[210:211], s[44:45], 0, v[134:135]
	s_addc_u32 vcc_hi, s45, 0
	s_add_i32 s85, s85, s49
	v_lshl_add_u64 v[212:213], vcc, 0, v[0:1]
	s_mov_b32 m0, s85
	v_lshl_add_u64 v[214:215], s[58:59], 0, v[132:133]
	v_lshl_add_u64 v[212:213], vcc, 0, v[134:135]
	s_add_i32 m0, s85, 0x2000
	s_nop 0
	v_lshl_add_u64 v[212:213], s[58:59], 0, v[130:131]
	s_mov_b32 m0, s9
	s_nop 0
	s_mov_b32 m0, s56
	s_nop 0
	s_waitcnt vmcnt(2)
	s_waitcnt lgkmcnt(0)
	s_barrier
	s_setprio 1
	s_waitcnt lgkmcnt(0)
	v_mfma_f32_16x16x32_bf16 v[62:65], v[142:145], v[174:177], v[62:65]
	v_mfma_f32_16x16x32_bf16 v[58:61], v[150:153], v[174:177], v[58:61]
	v_mfma_f32_16x16x32_bf16 v[54:57], v[142:145], v[182:185], v[54:57]
	v_mfma_f32_16x16x32_bf16 v[50:53], v[150:153], v[182:185], v[50:53]
	v_mfma_f32_16x16x32_bf16 v[38:41], v[142:145], v[192:195], v[38:41]
	v_mfma_f32_16x16x32_bf16 v[34:37], v[150:153], v[192:195], v[34:37]
	v_mfma_f32_16x16x32_bf16 v[22:25], v[142:145], v[200:203], v[22:25]
	v_mfma_f32_16x16x32_bf16 v[18:21], v[150:153], v[200:203], v[18:21]
	v_mfma_f32_16x16x32_bf16 v[62:65], v[146:149], v[178:181], v[62:65]
	v_mfma_f32_16x16x32_bf16 v[58:61], v[154:157], v[178:181], v[58:61]
	v_mfma_f32_16x16x32_bf16 v[54:57], v[146:149], v[186:189], v[54:57]
	v_mfma_f32_16x16x32_bf16 v[50:53], v[154:157], v[186:189], v[50:53]
	v_mfma_f32_16x16x32_bf16 v[38:41], v[146:149], v[196:199], v[38:41]
	v_mfma_f32_16x16x32_bf16 v[34:37], v[154:157], v[196:199], v[34:37]
	v_mfma_f32_16x16x32_bf16 v[22:25], v[146:149], v[204:207], v[22:25]
	v_mfma_f32_16x16x32_bf16 v[18:21], v[154:157], v[204:207], v[18:21]
	s_setprio 0
	s_setprio 1
	v_mfma_f32_16x16x32_bf16 v[46:49], v[158:161], v[174:177], v[46:49]
	v_mfma_f32_16x16x32_bf16 v[42:45], v[166:169], v[174:177], v[42:45]
	v_mfma_f32_16x16x32_bf16 v[30:33], v[158:161], v[182:185], v[30:33]
	v_mfma_f32_16x16x32_bf16 v[26:29], v[166:169], v[182:185], v[26:29]
	v_mfma_f32_16x16x32_bf16 v[14:17], v[158:161], v[192:195], v[14:17]
	v_mfma_f32_16x16x32_bf16 v[10:13], v[166:169], v[192:195], v[10:13]
	v_mfma_f32_16x16x32_bf16 v[6:9], v[158:161], v[200:203], v[6:9]
	v_mfma_f32_16x16x32_bf16 v[2:5], v[166:169], v[200:203], v[2:5]
	v_mfma_f32_16x16x32_bf16 v[46:49], v[162:165], v[178:181], v[46:49]
	v_mfma_f32_16x16x32_bf16 v[42:45], v[170:173], v[178:181], v[42:45]
	v_mfma_f32_16x16x32_bf16 v[30:33], v[162:165], v[186:189], v[30:33]
	v_mfma_f32_16x16x32_bf16 v[26:29], v[170:173], v[186:189], v[26:29]
	v_mfma_f32_16x16x32_bf16 v[14:17], v[162:165], v[196:199], v[14:17]
	v_mfma_f32_16x16x32_bf16 v[10:13], v[170:173], v[196:199], v[10:13]
	v_mfma_f32_16x16x32_bf16 v[6:9], v[162:165], v[204:207], v[6:9]
	v_mfma_f32_16x16x32_bf16 v[2:5], v[170:173], v[204:207], v[2:5]
	s_setprio 0
	s_barrier
	s_add_i32 s85, 0, 0x18000
	s_add_i32 s93, 0, 0x1c000
	v_add_u32_e32 v154, s85, v140
	v_add_u32_e32 v170, s93, v140
	ds_read_b128 v[142:145], v154
	ds_read_b128 v[146:149], v154 offset:1024
	ds_read_b128 v[150:153], v154 offset:2048
	ds_read_b128 v[154:157], v154 offset:3072
	ds_read_b128 v[158:161], v170
	ds_read_b128 v[162:165], v170 offset:1024
	ds_read_b128 v[166:169], v170 offset:2048
	ds_read_b128 v[170:173], v170 offset:3072
	s_add_u32 s58, s58, 0x40000
	s_addc_u32 s59, s59, 0
	s_mov_b32 m0, s57
	v_lshl_add_u64 v[216:217], s[58:59], 0, v[130:131]
	ds_read_b128 v[174:177], v141 offset:32768
	ds_read_b128 v[178:181], v141 offset:33792
	ds_read_b128 v[182:185], v141 offset:34816
	ds_read_b128 v[186:189], v141 offset:35840
	ds_read_b128 v[192:195], v141 offset:36864
	ds_read_b128 v[196:199], v141 offset:37888
	ds_read_b128 v[200:203], v141 offset:38912
	ds_read_b128 v[204:207], v141 offset:39936
	v_lshl_add_u64 v[216:217], s[58:59], 0, v[132:133]
	s_mov_b32 m0, s66
	s_nop 0
	s_waitcnt vmcnt(0)
	s_waitcnt lgkmcnt(0)
	s_barrier
	s_setprio 1
	s_waitcnt lgkmcnt(0)
	v_mfma_f32_16x16x32_bf16 v[126:129], v[142:145], v[174:177], v[126:129]
	v_mfma_f32_16x16x32_bf16 v[122:125], v[150:153], v[174:177], v[122:125]
	v_mfma_f32_16x16x32_bf16 v[118:121], v[142:145], v[182:185], v[118:121]
	v_mfma_f32_16x16x32_bf16 v[114:117], v[150:153], v[182:185], v[114:117]
	v_mfma_f32_16x16x32_bf16 v[102:105], v[142:145], v[192:195], v[102:105]
	v_mfma_f32_16x16x32_bf16 v[98:101], v[150:153], v[192:195], v[98:101]
	v_mfma_f32_16x16x32_bf16 v[86:89], v[142:145], v[200:203], v[86:89]
	v_mfma_f32_16x16x32_bf16 v[82:85], v[150:153], v[200:203], v[82:85]
	v_mfma_f32_16x16x32_bf16 v[126:129], v[146:149], v[178:181], v[126:129]
	v_mfma_f32_16x16x32_bf16 v[122:125], v[154:157], v[178:181], v[122:125]
	v_mfma_f32_16x16x32_bf16 v[118:121], v[146:149], v[186:189], v[118:121]
	v_mfma_f32_16x16x32_bf16 v[114:117], v[154:157], v[186:189], v[114:117]
	v_mfma_f32_16x16x32_bf16 v[102:105], v[146:149], v[196:199], v[102:105]
	v_mfma_f32_16x16x32_bf16 v[98:101], v[154:157], v[196:199], v[98:101]
	v_mfma_f32_16x16x32_bf16 v[86:89], v[146:149], v[204:207], v[86:89]
	v_mfma_f32_16x16x32_bf16 v[82:85], v[154:157], v[204:207], v[82:85]
	s_setprio 0
	s_setprio 1
	v_mfma_f32_16x16x32_bf16 v[110:113], v[158:161], v[174:177], v[110:113]
	v_mfma_f32_16x16x32_bf16 v[106:109], v[166:169], v[174:177], v[106:109]
	v_mfma_f32_16x16x32_bf16 v[94:97], v[158:161], v[182:185], v[94:97]
	v_mfma_f32_16x16x32_bf16 v[90:93], v[166:169], v[182:185], v[90:93]
	v_mfma_f32_16x16x32_bf16 v[78:81], v[158:161], v[192:195], v[78:81]
	v_mfma_f32_16x16x32_bf16 v[74:77], v[166:169], v[192:195], v[74:77]
	v_mfma_f32_16x16x32_bf16 v[70:73], v[158:161], v[200:203], v[70:73]
	v_mfma_f32_16x16x32_bf16 v[66:69], v[166:169], v[200:203], v[66:69]
	v_mfma_f32_16x16x32_bf16 v[110:113], v[162:165], v[178:181], v[110:113]
	v_mfma_f32_16x16x32_bf16 v[106:109], v[170:173], v[178:181], v[106:109]
	v_mfma_f32_16x16x32_bf16 v[94:97], v[162:165], v[186:189], v[94:97]
	v_mfma_f32_16x16x32_bf16 v[90:93], v[170:173], v[186:189], v[90:93]
	v_mfma_f32_16x16x32_bf16 v[78:81], v[162:165], v[196:199], v[78:81]
	v_mfma_f32_16x16x32_bf16 v[74:77], v[170:173], v[196:199], v[74:77]
	v_mfma_f32_16x16x32_bf16 v[70:73], v[162:165], v[204:207], v[70:73]
	v_mfma_f32_16x16x32_bf16 v[66:69], v[170:173], v[204:207], v[66:69]
	s_setprio 0
	s_barrier
	s_add_i32 s58, s85, s49
	v_lshl_add_u64 v[208:209], v[208:209], 0, s[86:87]
	s_mov_b32 m0, s58
	ds_read_b128 v[174:177], v141 offset:49152
	ds_read_b128 v[178:181], v141 offset:50176
	ds_read_b128 v[182:185], v141 offset:51200
	ds_read_b128 v[186:189], v141 offset:52224
	ds_read_b128 v[192:195], v141 offset:53248
	ds_read_b128 v[196:199], v141 offset:54272
	ds_read_b128 v[200:203], v141 offset:55296
	ds_read_b128 v[204:207], v141 offset:56320
	s_add_i32 m0, s58, 0x2000
	s_add_u32 s44, s44, 0x40080
	v_lshl_add_u64 v[208:209], v[210:211], 0, s[86:87]
	s_addc_u32 s45, s45, 0
	s_add_i32 s58, s93, s49
	v_lshl_add_u64 v[208:209], s[44:45], 0, v[0:1]
	s_mov_b32 m0, s58
	s_nop 0
	v_lshl_add_u64 v[208:209], s[44:45], 0, v[134:135]
	s_add_i32 m0, s58, 0x2000
	s_nop 0
	v_lshl_add_u64 v[208:209], v[212:213], 0, s[86:87]
	s_mov_b32 m0, s71
	s_nop 0
	v_lshl_add_u64 v[208:209], v[214:215], 0, s[86:87]
	s_mov_b32 m0, s74
	s_nop 0
	s_waitcnt vmcnt(0)
	s_waitcnt lgkmcnt(0)
	s_barrier
	s_setprio 1
	s_waitcnt lgkmcnt(0)
	v_mfma_f32_16x16x32_bf16 v[62:65], v[142:145], v[174:177], v[62:65]
	v_mfma_f32_16x16x32_bf16 v[58:61], v[150:153], v[174:177], v[58:61]
	v_mfma_f32_16x16x32_bf16 v[54:57], v[142:145], v[182:185], v[54:57]
	v_mfma_f32_16x16x32_bf16 v[50:53], v[150:153], v[182:185], v[50:53]
	v_mfma_f32_16x16x32_bf16 v[38:41], v[142:145], v[192:195], v[38:41]
	v_mfma_f32_16x16x32_bf16 v[34:37], v[150:153], v[192:195], v[34:37]
	v_mfma_f32_16x16x32_bf16 v[22:25], v[142:145], v[200:203], v[22:25]
	v_mfma_f32_16x16x32_bf16 v[18:21], v[150:153], v[200:203], v[18:21]
	v_mfma_f32_16x16x32_bf16 v[62:65], v[146:149], v[178:181], v[62:65]
	v_mfma_f32_16x16x32_bf16 v[58:61], v[154:157], v[178:181], v[58:61]
	v_mfma_f32_16x16x32_bf16 v[54:57], v[146:149], v[186:189], v[54:57]
	v_mfma_f32_16x16x32_bf16 v[50:53], v[154:157], v[186:189], v[50:53]
	v_mfma_f32_16x16x32_bf16 v[38:41], v[146:149], v[196:199], v[38:41]
	v_mfma_f32_16x16x32_bf16 v[34:37], v[154:157], v[196:199], v[34:37]
	v_mfma_f32_16x16x32_bf16 v[22:25], v[146:149], v[204:207], v[22:25]
	v_mfma_f32_16x16x32_bf16 v[18:21], v[154:157], v[204:207], v[18:21]
	s_setprio 0
	s_setprio 1
	v_mfma_f32_16x16x32_bf16 v[46:49], v[158:161], v[174:177], v[46:49]
	v_mfma_f32_16x16x32_bf16 v[42:45], v[166:169], v[174:177], v[42:45]
	v_mfma_f32_16x16x32_bf16 v[30:33], v[158:161], v[182:185], v[30:33]
	v_mfma_f32_16x16x32_bf16 v[26:29], v[166:169], v[182:185], v[26:29]
	v_mfma_f32_16x16x32_bf16 v[14:17], v[158:161], v[192:195], v[14:17]
	v_mfma_f32_16x16x32_bf16 v[10:13], v[166:169], v[192:195], v[10:13]
	v_mfma_f32_16x16x32_bf16 v[6:9], v[158:161], v[200:203], v[6:9]
	v_mfma_f32_16x16x32_bf16 v[2:5], v[166:169], v[200:203], v[2:5]
	v_mfma_f32_16x16x32_bf16 v[46:49], v[162:165], v[178:181], v[46:49]
	v_mfma_f32_16x16x32_bf16 v[42:45], v[170:173], v[178:181], v[42:45]
	v_mfma_f32_16x16x32_bf16 v[30:33], v[162:165], v[186:189], v[30:33]
	v_mfma_f32_16x16x32_bf16 v[26:29], v[170:173], v[186:189], v[26:29]
	v_mfma_f32_16x16x32_bf16 v[14:17], v[162:165], v[196:199], v[14:17]
	v_mfma_f32_16x16x32_bf16 v[10:13], v[170:173], v[196:199], v[10:13]
	v_mfma_f32_16x16x32_bf16 v[6:9], v[162:165], v[204:207], v[6:9]
	v_mfma_f32_16x16x32_bf16 v[2:5], v[170:173], v[204:207], v[2:5]
	s_setprio 0
	s_barrier
	s_add_i32 s81, s81, 2
	s_add_u32 s38, s38, 0x100
	s_addc_u32 s39, s39, 0
	s_cmp_lt_u32 s81, 14
	s_waitcnt vmcnt(0)
	s_cmpk_gt_u32 s40, 0xff
	s_cbranch_scc1 .LBB0_163
	s_barrier

.LBB0_234:
	s_ashr_i32 s23, s22, 31
	s_lshl_b64 s[24:25], s[22:23], 19
	s_add_u32 s24, s3, s24
	s_addc_u32 s25, s4, s25
	s_and_b64 s[26:27], s[8:9], exec
	s_cselect_b32 s23, s25, s29
	s_cselect_b32 s77, s24, s28
	s_ashr_i32 s21, s20, 31
	s_lshl_b64 s[26:27], s[20:21], 19
	s_add_u32 s26, s5, s26
	s_addc_u32 s27, s30, s27
	s_and_b64 s[44:45], s[8:9], exec
	s_cselect_b32 s21, s27, s39
	s_cselect_b32 s78, s26, s38
	s_add_u32 s79, s38, 0x100
	s_addc_u32 s81, s39, 0
	s_mov_b32 s85, -2
	s_nop 0
	s_add_u32 s38, s28, 0x100
	s_addc_u32 s39, s29, 0
	s_add_i32 s93, 0, 0x10000
	s_cmp_eq_u32 s85, 12
	s_cselect_b32 s59, s23, s39
	s_cselect_b32 s58, s77, s38
	s_cselect_b32 s45, s21, s81
	s_cselect_b32 s44, s78, s79
	s_add_i32 vcc_lo, 0, 0x14000
	v_add_u32_e32 v142, s93, v158
	v_add_u32_e32 v156, vcc_lo, v158
	ds_read_b128 v[130:133], v142
	ds_read_b128 v[134:137], v142 offset:1024
	ds_read_b128 v[138:141], v142 offset:2048
	ds_read_b128 v[142:145], v142 offset:3072
	ds_read_b128 v[152:155], v156
	ds_read_b128 v[160:163], v156 offset:1024
	ds_read_b128 v[164:167], v156 offset:2048
	ds_read_b128 v[168:171], v156 offset:3072
	v_lshl_add_u64 v[156:157], s[28:29], 0, v[148:149]
	s_add_i32 m0, s42, 0xc000
	ds_read_b128 v[172:175], v159
	ds_read_b128 v[176:179], v159 offset:1024
	ds_read_b128 v[180:183], v159 offset:2048
	ds_read_b128 v[184:187], v159 offset:3072
	ds_read_b128 v[196:199], v159 offset:4096
	ds_read_b128 v[200:203], v159 offset:5120
	ds_read_b128 v[204:207], v159 offset:6144
	ds_read_b128 v[208:211], v159 offset:7168
	global_load_lds_dwordx4 v[156:157], off
	v_lshl_add_u64 v[156:157], s[28:29], 0, v[150:151]
	s_add_i32 m0, s42, 0xe000
	s_nop 0
	global_load_lds_dwordx4 v[156:157], off
	s_waitcnt vmcnt(8)
	s_waitcnt lgkmcnt(0)
	s_barrier
	s_setprio 1
	s_waitcnt lgkmcnt(0)
	v_mfma_f32_16x16x32_bf16 v[126:129], v[130:133], v[172:175], 0
	v_mfma_f32_16x16x32_bf16 v[122:125], v[138:141], v[172:175], 0
	v_mfma_f32_16x16x32_bf16 v[114:117], v[130:133], v[180:183], 0
	v_mfma_f32_16x16x32_bf16 v[110:113], v[138:141], v[180:183], 0
	v_mfma_f32_16x16x32_bf16 v[94:97], v[130:133], v[196:199], 0
	v_mfma_f32_16x16x32_bf16 v[90:93], v[138:141], v[196:199], 0
	v_mfma_f32_16x16x32_bf16 v[86:89], v[130:133], v[204:207], 0
	v_mfma_f32_16x16x32_bf16 v[78:81], v[138:141], v[204:207], 0
	v_mfma_f32_16x16x32_bf16 v[126:129], v[134:137], v[176:179], v[126:129]
	v_mfma_f32_16x16x32_bf16 v[122:125], v[142:145], v[176:179], v[122:125]
	v_mfma_f32_16x16x32_bf16 v[114:117], v[134:137], v[184:187], v[114:117]
	v_mfma_f32_16x16x32_bf16 v[110:113], v[142:145], v[184:187], v[110:113]
	v_mfma_f32_16x16x32_bf16 v[94:97], v[134:137], v[200:203], v[94:97]
	v_mfma_f32_16x16x32_bf16 v[90:93], v[142:145], v[200:203], v[90:93]
	v_mfma_f32_16x16x32_bf16 v[86:89], v[134:137], v[208:211], v[86:89]
	v_mfma_f32_16x16x32_bf16 v[78:81], v[142:145], v[208:211], v[78:81]
	s_setprio 0
	s_setprio 1
	v_mfma_f32_16x16x32_bf16 v[118:121], v[152:155], v[172:175], 0
	v_mfma_f32_16x16x32_bf16 v[106:109], v[164:167], v[172:175], 0
	v_mfma_f32_16x16x32_bf16 v[102:105], v[152:155], v[180:183], 0
	v_mfma_f32_16x16x32_bf16 v[98:101], v[164:167], v[180:183], 0
	v_mfma_f32_16x16x32_bf16 v[82:85], v[152:155], v[196:199], 0
	v_mfma_f32_16x16x32_bf16 v[74:77], v[164:167], v[196:199], 0
	v_mfma_f32_16x16x32_bf16 v[70:73], v[152:155], v[204:207], 0
	v_mfma_f32_16x16x32_bf16 v[66:69], v[164:167], v[204:207], 0
	v_mfma_f32_16x16x32_bf16 v[118:121], v[160:163], v[176:179], v[118:121]
	v_mfma_f32_16x16x32_bf16 v[106:109], v[168:171], v[176:179], v[106:109]
	v_mfma_f32_16x16x32_bf16 v[102:105], v[160:163], v[184:187], v[102:105]
	v_mfma_f32_16x16x32_bf16 v[98:101], v[168:171], v[184:187], v[98:101]
	v_mfma_f32_16x16x32_bf16 v[82:85], v[160:163], v[200:203], v[82:85]
	v_mfma_f32_16x16x32_bf16 v[74:77], v[168:171], v[200:203], v[74:77]
	v_mfma_f32_16x16x32_bf16 v[70:73], v[160:163], v[208:211], v[70:73]
	v_mfma_f32_16x16x32_bf16 v[66:69], v[168:171], v[208:211], v[66:69]
	s_setprio 0
	s_barrier
	s_add_i32 s28, s93, s40
	v_lshl_add_u64 v[156:157], s[44:45], 0, v[0:1]
	s_mov_b32 m0, s28
	ds_read_b128 v[172:175], v159 offset:16384
	ds_read_b128 v[176:179], v159 offset:17408
	ds_read_b128 v[180:183], v159 offset:18432
	ds_read_b128 v[184:187], v159 offset:19456
	ds_read_b128 v[196:199], v159 offset:20480
	ds_read_b128 v[200:203], v159 offset:21504
	ds_read_b128 v[204:207], v159 offset:22528
	ds_read_b128 v[208:211], v159 offset:23552
	global_load_lds_dwordx4 v[156:157], off
	s_add_i32 m0, s28, 0x2000
	s_add_u32 s28, s44, 0x40000
	v_lshl_add_u64 v[188:189], s[44:45], 0, v[146:147]
	s_addc_u32 s29, s45, 0
	s_add_i32 s93, vcc_lo, s40
	global_load_lds_dwordx4 v[188:189], off
	v_lshl_add_u64 v[192:193], s[28:29], 0, v[0:1]
	s_mov_b32 m0, s93
	v_lshl_add_u64 v[194:195], s[58:59], 0, v[146:147]
	global_load_lds_dwordx4 v[192:193], off
	v_lshl_add_u64 v[192:193], s[28:29], 0, v[146:147]
	s_add_i32 m0, s93, 0x2000
	s_nop 0
	global_load_lds_dwordx4 v[192:193], off
	v_lshl_add_u64 v[192:193], s[58:59], 0, v[0:1]
	s_mov_b32 m0, s42
	s_nop 0
	global_load_lds_dwordx4 v[192:193], off
	s_mov_b32 m0, s43
	s_nop 0
	global_load_lds_dwordx4 v[194:195], off
	s_waitcnt vmcnt(8)
	s_waitcnt lgkmcnt(0)
	s_barrier
	s_setprio 1
	s_waitcnt lgkmcnt(0)
	v_mfma_f32_16x16x32_bf16 v[62:65], v[130:133], v[172:175], 0
	v_mfma_f32_16x16x32_bf16 v[58:61], v[138:141], v[172:175], 0
	v_mfma_f32_16x16x32_bf16 v[54:57], v[130:133], v[180:183], 0
	v_mfma_f32_16x16x32_bf16 v[46:49], v[138:141], v[180:183], 0
	v_mfma_f32_16x16x32_bf16 v[34:37], v[130:133], v[196:199], 0
	v_mfma_f32_16x16x32_bf16 v[26:29], v[138:141], v[196:199], 0
	v_mfma_f32_16x16x32_bf16 v[22:25], v[130:133], v[204:207], 0
	v_mfma_f32_16x16x32_bf16 v[14:17], v[138:141], v[204:207], 0
	v_mfma_f32_16x16x32_bf16 v[62:65], v[134:137], v[176:179], v[62:65]
	v_mfma_f32_16x16x32_bf16 v[58:61], v[142:145], v[176:179], v[58:61]
	v_mfma_f32_16x16x32_bf16 v[54:57], v[134:137], v[184:187], v[54:57]
	v_mfma_f32_16x16x32_bf16 v[46:49], v[142:145], v[184:187], v[46:49]
	v_mfma_f32_16x16x32_bf16 v[34:37], v[134:137], v[200:203], v[34:37]
	v_mfma_f32_16x16x32_bf16 v[26:29], v[142:145], v[200:203], v[26:29]
	v_mfma_f32_16x16x32_bf16 v[22:25], v[134:137], v[208:211], v[22:25]
	v_mfma_f32_16x16x32_bf16 v[14:17], v[142:145], v[208:211], v[14:17]
	s_setprio 0
	s_setprio 1
	v_mfma_f32_16x16x32_bf16 v[50:53], v[152:155], v[172:175], 0
	v_mfma_f32_16x16x32_bf16 v[42:45], v[164:167], v[172:175], 0
	v_mfma_f32_16x16x32_bf16 v[38:41], v[152:155], v[180:183], 0
	v_mfma_f32_16x16x32_bf16 v[30:33], v[164:167], v[180:183], 0
	v_mfma_f32_16x16x32_bf16 v[18:21], v[152:155], v[196:199], 0
	v_mfma_f32_16x16x32_bf16 v[10:13], v[164:167], v[196:199], 0
	v_mfma_f32_16x16x32_bf16 v[6:9], v[152:155], v[204:207], 0
	v_mfma_f32_16x16x32_bf16 v[2:5], v[164:167], v[204:207], 0
	v_mfma_f32_16x16x32_bf16 v[50:53], v[160:163], v[176:179], v[50:53]
	v_mfma_f32_16x16x32_bf16 v[42:45], v[168:171], v[176:179], v[42:45]
	v_mfma_f32_16x16x32_bf16 v[38:41], v[160:163], v[184:187], v[38:41]
	v_mfma_f32_16x16x32_bf16 v[30:33], v[168:171], v[184:187], v[30:33]
	v_mfma_f32_16x16x32_bf16 v[18:21], v[160:163], v[200:203], v[18:21]
	v_mfma_f32_16x16x32_bf16 v[10:13], v[168:171], v[200:203], v[10:13]
	v_mfma_f32_16x16x32_bf16 v[6:9], v[160:163], v[208:211], v[6:9]
	v_mfma_f32_16x16x32_bf16 v[2:5], v[168:171], v[208:211], v[2:5]
	s_setprio 0
	s_barrier
	s_add_i32 s93, 0, 0x18000
	s_add_i32 vcc_lo, 0, 0x1c000
	v_add_u32_e32 v142, s93, v158
	v_add_u32_e32 v168, vcc_lo, v158
	ds_read_b128 v[130:133], v142
	ds_read_b128 v[134:137], v142 offset:1024
	ds_read_b128 v[138:141], v142 offset:2048
	ds_read_b128 v[142:145], v142 offset:3072
	ds_read_b128 v[152:155], v168
	ds_read_b128 v[160:163], v168 offset:1024
	ds_read_b128 v[164:167], v168 offset:2048
	ds_read_b128 v[168:171], v168 offset:3072
	s_add_u32 s28, s58, 0x40000
	s_addc_u32 s29, s59, 0
	s_mov_b32 m0, s46
	v_lshl_add_u64 v[212:213], s[28:29], 0, v[0:1]
	ds_read_b128 v[172:175], v159 offset:32768
	ds_read_b128 v[176:179], v159 offset:33792
	ds_read_b128 v[180:183], v159 offset:34816
	ds_read_b128 v[184:187], v159 offset:35840
	ds_read_b128 v[196:199], v159 offset:36864
	ds_read_b128 v[200:203], v159 offset:37888
	ds_read_b128 v[204:207], v159 offset:38912
	ds_read_b128 v[208:211], v159 offset:39936
	global_load_lds_dwordx4 v[212:213], off
	v_lshl_add_u64 v[212:213], s[28:29], 0, v[146:147]
	s_mov_b32 m0, s48
	s_nop 0
	global_load_lds_dwordx4 v[212:213], off
	s_waitcnt vmcnt(8)
	s_waitcnt lgkmcnt(0)
	s_barrier
	s_setprio 1
	s_waitcnt lgkmcnt(0)
	v_mfma_f32_16x16x32_bf16 v[126:129], v[130:133], v[172:175], v[126:129]
	v_mfma_f32_16x16x32_bf16 v[122:125], v[138:141], v[172:175], v[122:125]
	v_mfma_f32_16x16x32_bf16 v[114:117], v[130:133], v[180:183], v[114:117]
	v_mfma_f32_16x16x32_bf16 v[110:113], v[138:141], v[180:183], v[110:113]
	v_mfma_f32_16x16x32_bf16 v[94:97], v[130:133], v[196:199], v[94:97]
	v_mfma_f32_16x16x32_bf16 v[90:93], v[138:141], v[196:199], v[90:93]
	v_mfma_f32_16x16x32_bf16 v[86:89], v[130:133], v[204:207], v[86:89]
	v_mfma_f32_16x16x32_bf16 v[78:81], v[138:141], v[204:207], v[78:81]
	v_mfma_f32_16x16x32_bf16 v[126:129], v[134:137], v[176:179], v[126:129]
	v_mfma_f32_16x16x32_bf16 v[122:125], v[142:145], v[176:179], v[122:125]
	v_mfma_f32_16x16x32_bf16 v[114:117], v[134:137], v[184:187], v[114:117]
	v_mfma_f32_16x16x32_bf16 v[110:113], v[142:145], v[184:187], v[110:113]
	v_mfma_f32_16x16x32_bf16 v[94:97], v[134:137], v[200:203], v[94:97]
	v_mfma_f32_16x16x32_bf16 v[90:93], v[142:145], v[200:203], v[90:93]
	v_mfma_f32_16x16x32_bf16 v[86:89], v[134:137], v[208:211], v[86:89]
	v_mfma_f32_16x16x32_bf16 v[78:81], v[142:145], v[208:211], v[78:81]
	s_setprio 0
	s_setprio 1
	v_mfma_f32_16x16x32_bf16 v[118:121], v[152:155], v[172:175], v[118:121]
	v_mfma_f32_16x16x32_bf16 v[106:109], v[164:167], v[172:175], v[106:109]
	v_mfma_f32_16x16x32_bf16 v[102:105], v[152:155], v[180:183], v[102:105]
	v_mfma_f32_16x16x32_bf16 v[98:101], v[164:167], v[180:183], v[98:101]
	v_mfma_f32_16x16x32_bf16 v[82:85], v[152:155], v[196:199], v[82:85]
	v_mfma_f32_16x16x32_bf16 v[74:77], v[164:167], v[196:199], v[74:77]
	v_mfma_f32_16x16x32_bf16 v[70:73], v[152:155], v[204:207], v[70:73]
	v_mfma_f32_16x16x32_bf16 v[66:69], v[164:167], v[204:207], v[66:69]
	v_mfma_f32_16x16x32_bf16 v[118:121], v[160:163], v[176:179], v[118:121]
	v_mfma_f32_16x16x32_bf16 v[106:109], v[168:171], v[176:179], v[106:109]
	v_mfma_f32_16x16x32_bf16 v[102:105], v[160:163], v[184:187], v[102:105]
	v_mfma_f32_16x16x32_bf16 v[98:101], v[168:171], v[184:187], v[98:101]
	v_mfma_f32_16x16x32_bf16 v[82:85], v[160:163], v[200:203], v[82:85]
	v_mfma_f32_16x16x32_bf16 v[74:77], v[168:171], v[200:203], v[74:77]
	v_mfma_f32_16x16x32_bf16 v[70:73], v[160:163], v[208:211], v[70:73]
	v_mfma_f32_16x16x32_bf16 v[66:69], v[168:171], v[208:211], v[66:69]
	s_setprio 0
	s_barrier
	s_add_i32 s28, s93, s40
	v_lshl_add_u64 v[156:157], v[156:157], 0, s[86:87]
	s_mov_b32 m0, s28
	ds_read_b128 v[172:175], v159 offset:49152
	ds_read_b128 v[176:179], v159 offset:50176
	ds_read_b128 v[180:183], v159 offset:51200
	ds_read_b128 v[184:187], v159 offset:52224
	ds_read_b128 v[196:199], v159 offset:53248
	ds_read_b128 v[200:203], v159 offset:54272
	ds_read_b128 v[204:207], v159 offset:55296
	ds_read_b128 v[208:211], v159 offset:56320
	global_load_lds_dwordx4 v[156:157], off
	s_add_i32 m0, s28, 0x2000
	s_add_u32 s28, s44, 0x40080
	v_lshl_add_u64 v[156:157], v[188:189], 0, s[86:87]
	s_addc_u32 s29, s45, 0
	s_add_i32 s44, vcc_lo, s40
	global_load_lds_dwordx4 v[156:157], off
	v_lshl_add_u64 v[156:157], s[28:29], 0, v[0:1]
	s_mov_b32 m0, s44
	s_nop 0
	global_load_lds_dwordx4 v[156:157], off
	v_lshl_add_u64 v[156:157], s[28:29], 0, v[146:147]
	s_add_i32 m0, s44, 0x2000
	s_nop 0
	global_load_lds_dwordx4 v[156:157], off
	v_lshl_add_u64 v[156:157], v[192:193], 0, s[86:87]
	s_mov_b32 m0, s67
	s_nop 0
	global_load_lds_dwordx4 v[156:157], off
	v_lshl_add_u64 v[156:157], v[194:195], 0, s[86:87]
	s_mov_b32 m0, s70
	s_nop 0
	global_load_lds_dwordx4 v[156:157], off
	s_waitcnt vmcnt(8)
	s_waitcnt lgkmcnt(0)
	s_barrier
	s_setprio 1
	s_waitcnt lgkmcnt(0)
	v_mfma_f32_16x16x32_bf16 v[62:65], v[130:133], v[172:175], v[62:65]
	v_mfma_f32_16x16x32_bf16 v[58:61], v[138:141], v[172:175], v[58:61]
	v_mfma_f32_16x16x32_bf16 v[54:57], v[130:133], v[180:183], v[54:57]
	v_mfma_f32_16x16x32_bf16 v[46:49], v[138:141], v[180:183], v[46:49]
	v_mfma_f32_16x16x32_bf16 v[34:37], v[130:133], v[196:199], v[34:37]
	v_mfma_f32_16x16x32_bf16 v[26:29], v[138:141], v[196:199], v[26:29]
	v_mfma_f32_16x16x32_bf16 v[22:25], v[130:133], v[204:207], v[22:25]
	v_mfma_f32_16x16x32_bf16 v[14:17], v[138:141], v[204:207], v[14:17]
	v_mfma_f32_16x16x32_bf16 v[62:65], v[134:137], v[176:179], v[62:65]
	v_mfma_f32_16x16x32_bf16 v[58:61], v[142:145], v[176:179], v[58:61]
	v_mfma_f32_16x16x32_bf16 v[54:57], v[134:137], v[184:187], v[54:57]
	v_mfma_f32_16x16x32_bf16 v[46:49], v[142:145], v[184:187], v[46:49]
	v_mfma_f32_16x16x32_bf16 v[34:37], v[134:137], v[200:203], v[34:37]
	v_mfma_f32_16x16x32_bf16 v[26:29], v[142:145], v[200:203], v[26:29]
	v_mfma_f32_16x16x32_bf16 v[22:25], v[134:137], v[208:211], v[22:25]
	v_mfma_f32_16x16x32_bf16 v[14:17], v[142:145], v[208:211], v[14:17]
	s_setprio 0
	s_setprio 1
	v_mfma_f32_16x16x32_bf16 v[50:53], v[152:155], v[172:175], v[50:53]
	v_mfma_f32_16x16x32_bf16 v[42:45], v[164:167], v[172:175], v[42:45]
	v_mfma_f32_16x16x32_bf16 v[38:41], v[152:155], v[180:183], v[38:41]
	v_mfma_f32_16x16x32_bf16 v[30:33], v[164:167], v[180:183], v[30:33]
	v_mfma_f32_16x16x32_bf16 v[18:21], v[152:155], v[196:199], v[18:21]
	v_mfma_f32_16x16x32_bf16 v[10:13], v[164:167], v[196:199], v[10:13]
	v_mfma_f32_16x16x32_bf16 v[6:9], v[152:155], v[204:207], v[6:9]
	v_mfma_f32_16x16x32_bf16 v[2:5], v[164:167], v[204:207], v[2:5]
	v_mfma_f32_16x16x32_bf16 v[50:53], v[160:163], v[176:179], v[50:53]
	v_mfma_f32_16x16x32_bf16 v[42:45], v[168:171], v[176:179], v[42:45]
	v_mfma_f32_16x16x32_bf16 v[38:41], v[160:163], v[184:187], v[38:41]
	v_mfma_f32_16x16x32_bf16 v[30:33], v[168:171], v[184:187], v[30:33]
	v_mfma_f32_16x16x32_bf16 v[18:21], v[160:163], v[200:203], v[18:21]
	v_mfma_f32_16x16x32_bf16 v[10:13], v[168:171], v[200:203], v[10:13]
	v_mfma_f32_16x16x32_bf16 v[6:9], v[160:163], v[208:211], v[6:9]
	v_mfma_f32_16x16x32_bf16 v[2:5], v[168:171], v[208:211], v[2:5]
	s_setprio 0
	s_barrier
	s_add_i32 s85, s85, 2
	s_add_u32 s79, s79, 0x100
	s_addc_u32 s81, s81, 0
	s_cmp_gt_u32 s85, 13
	s_mov_b64 s[28:29], s[38:39]

.LBB0_458:
	s_ashr_i32 s29, s28, 31
	s_lshl_b64 s[14:15], s[28:29], 19
	v_readlane_b32 s3, v255, 54
	s_add_u32 s38, s3, s14
	v_readlane_b32 s3, v255, 55
	s_addc_u32 s39, s3, s15
	s_and_b64 s[14:15], s[6:7], exec
	s_cselect_b32 s3, s39, s11
	s_cselect_b32 s9, s38, s10
	s_ashr_i32 s27, s26, 31
	s_lshl_b64 s[14:15], s[26:27], 19
	v_readlane_b32 s13, v255, 50
	s_add_u32 s70, s13, s14
	v_readlane_b32 s13, v255, 51
	s_addc_u32 s71, s13, s15
	s_and_b64 s[14:15], s[6:7], exec
	s_cselect_b32 s13, s71, s59
	s_cselect_b32 s14, s70, s58
	s_add_u32 s10, s10, 0x40080
	s_addc_u32 s11, s11, 0
	s_add_u32 s15, s58, 0x100
	s_addc_u32 s27, s59, 0
	s_mov_b32 s29, -2
	s_nop 0
	s_add_u32 s33, s10, 0xfffc0080
	s_addc_u32 s40, s11, -1
	s_add_i32 s43, 0, 0x10000
	s_cmp_eq_u32 s29, 12
	s_cselect_b32 s67, s3, s40
	s_cselect_b32 s66, s9, s33
	v_add_u32_e32 v0, s43, v245
	s_cselect_b32 s59, s13, s27
	s_cselect_b32 s58, s14, s15
	s_add_i32 s33, 0, 0x14000
	ds_read_b128 v[130:133], v0
	ds_read_b128 v[134:137], v0 offset:1024
	ds_read_b128 v[138:141], v0 offset:2048
	ds_read_b128 v[142:145], v0 offset:3072
	v_add_u32_e32 v0, s33, v245
	ds_read_b128 v[146:149], v0
	ds_read_b128 v[150:153], v0 offset:1024
	ds_read_b128 v[154:157], v0 offset:2048
	ds_read_b128 v[158:161], v0 offset:3072
	v_lshl_add_u64 v[192:193], s[10:11], 0, v[200:201]
	s_add_i32 m0, s31, 0xc000
	ds_read_b128 v[162:165], v246
	ds_read_b128 v[166:169], v246 offset:1024
	ds_read_b128 v[170:173], v246 offset:2048
	ds_read_b128 v[174:177], v246 offset:3072
	ds_read_b128 v[178:181], v246 offset:4096
	ds_read_b128 v[182:185], v246 offset:5120
	ds_read_b128 v[204:207], v246 offset:6144
	ds_read_b128 v[208:211], v246 offset:7168
	global_load_lds_dwordx4 v[192:193], off
	v_lshl_add_u64 v[192:193], s[10:11], 0, v[202:203]
	s_add_i32 m0, s31, 0xe000
	s_nop 0
	global_load_lds_dwordx4 v[192:193], off
	s_waitcnt vmcnt(8)
	s_waitcnt lgkmcnt(0)
	s_barrier
	s_setprio 1
	s_waitcnt lgkmcnt(0)
	v_mfma_f32_16x16x32_bf16 v[126:129], v[130:133], v[162:165], 0
	v_mfma_f32_16x16x32_bf16 v[122:125], v[138:141], v[162:165], 0
	v_mfma_f32_16x16x32_bf16 v[110:113], v[130:133], v[170:173], 0
	v_mfma_f32_16x16x32_bf16 v[106:109], v[138:141], v[170:173], 0
	v_mfma_f32_16x16x32_bf16 v[94:97], v[130:133], v[178:181], 0
	v_mfma_f32_16x16x32_bf16 v[90:93], v[138:141], v[178:181], 0
	v_mfma_f32_16x16x32_bf16 v[78:81], v[130:133], v[204:207], 0
	v_mfma_f32_16x16x32_bf16 v[74:77], v[138:141], v[204:207], 0
	v_mfma_f32_16x16x32_bf16 v[126:129], v[134:137], v[166:169], v[126:129]
	v_mfma_f32_16x16x32_bf16 v[122:125], v[142:145], v[166:169], v[122:125]
	v_mfma_f32_16x16x32_bf16 v[110:113], v[134:137], v[174:177], v[110:113]
	v_mfma_f32_16x16x32_bf16 v[106:109], v[142:145], v[174:177], v[106:109]
	v_mfma_f32_16x16x32_bf16 v[94:97], v[134:137], v[182:185], v[94:97]
	v_mfma_f32_16x16x32_bf16 v[90:93], v[142:145], v[182:185], v[90:93]
	v_mfma_f32_16x16x32_bf16 v[78:81], v[134:137], v[208:211], v[78:81]
	v_mfma_f32_16x16x32_bf16 v[74:77], v[142:145], v[208:211], v[74:77]
	s_setprio 0
	s_setprio 1
	v_mfma_f32_16x16x32_bf16 v[118:121], v[146:149], v[162:165], 0
	v_mfma_f32_16x16x32_bf16 v[114:117], v[154:157], v[162:165], 0
	v_mfma_f32_16x16x32_bf16 v[102:105], v[146:149], v[170:173], 0
	v_mfma_f32_16x16x32_bf16 v[98:101], v[154:157], v[170:173], 0
	v_mfma_f32_16x16x32_bf16 v[86:89], v[146:149], v[178:181], 0
	v_mfma_f32_16x16x32_bf16 v[82:85], v[154:157], v[178:181], 0
	v_mfma_f32_16x16x32_bf16 v[70:73], v[146:149], v[204:207], 0
	v_mfma_f32_16x16x32_bf16 v[66:69], v[154:157], v[204:207], 0
	v_mfma_f32_16x16x32_bf16 v[118:121], v[150:153], v[166:169], v[118:121]
	v_mfma_f32_16x16x32_bf16 v[114:117], v[158:161], v[166:169], v[114:117]
	v_mfma_f32_16x16x32_bf16 v[102:105], v[150:153], v[174:177], v[102:105]
	v_mfma_f32_16x16x32_bf16 v[98:101], v[158:161], v[174:177], v[98:101]
	v_mfma_f32_16x16x32_bf16 v[86:89], v[150:153], v[182:185], v[86:89]
	v_mfma_f32_16x16x32_bf16 v[82:85], v[158:161], v[182:185], v[82:85]
	v_mfma_f32_16x16x32_bf16 v[70:73], v[150:153], v[208:211], v[70:73]
	v_mfma_f32_16x16x32_bf16 v[66:69], v[158:161], v[208:211], v[66:69]
	s_setprio 0
	s_barrier
	s_add_i32 s40, s43, s30
	v_lshl_add_u64 v[192:193], s[58:59], 0, v[188:189]
	s_mov_b32 m0, s40
	ds_read_b128 v[162:165], v246 offset:16384
	ds_read_b128 v[166:169], v246 offset:17408
	ds_read_b128 v[170:173], v246 offset:18432
	ds_read_b128 v[174:177], v246 offset:19456
	ds_read_b128 v[178:181], v246 offset:20480
	ds_read_b128 v[182:185], v246 offset:21504
	ds_read_b128 v[204:207], v246 offset:22528
	ds_read_b128 v[208:211], v246 offset:23552
	global_load_lds_dwordx4 v[192:193], off
	s_add_i32 m0, s40, 0x2000
	s_add_u32 s48, s58, 0x40000
	v_lshl_add_u64 v[194:195], s[58:59], 0, v[198:199]
	s_addc_u32 s49, s59, 0
	s_add_i32 s33, s33, s30
	global_load_lds_dwordx4 v[194:195], off
	v_lshl_add_u64 v[212:213], s[48:49], 0, v[188:189]
	s_mov_b32 m0, s33
	v_lshl_add_u64 v[214:215], s[66:67], 0, v[196:197]
	global_load_lds_dwordx4 v[212:213], off
	v_lshl_add_u64 v[212:213], s[48:49], 0, v[198:199]
	s_add_i32 m0, s33, 0x2000
	s_nop 0
	global_load_lds_dwordx4 v[212:213], off
	v_lshl_add_u64 v[212:213], s[66:67], 0, v[186:187]
	s_mov_b32 m0, s31
	s_nop 0
	global_load_lds_dwordx4 v[212:213], off
	s_mov_b32 m0, s37
	s_nop 0
	global_load_lds_dwordx4 v[214:215], off
	s_waitcnt vmcnt(8)
	s_waitcnt lgkmcnt(0)
	s_barrier
	s_setprio 1
	s_waitcnt lgkmcnt(0)
	v_mfma_f32_16x16x32_bf16 v[62:65], v[130:133], v[162:165], 0
	v_mfma_f32_16x16x32_bf16 v[58:61], v[138:141], v[162:165], 0
	v_mfma_f32_16x16x32_bf16 v[46:49], v[130:133], v[170:173], 0
	v_mfma_f32_16x16x32_bf16 v[42:45], v[138:141], v[170:173], 0
	v_mfma_f32_16x16x32_bf16 v[30:33], v[130:133], v[178:181], 0
	v_mfma_f32_16x16x32_bf16 v[26:29], v[138:141], v[178:181], 0
	v_mfma_f32_16x16x32_bf16 v[14:17], v[130:133], v[204:207], 0
	v_mfma_f32_16x16x32_bf16 v[10:13], v[138:141], v[204:207], 0
	v_mfma_f32_16x16x32_bf16 v[62:65], v[134:137], v[166:169], v[62:65]
	v_mfma_f32_16x16x32_bf16 v[58:61], v[142:145], v[166:169], v[58:61]
	v_mfma_f32_16x16x32_bf16 v[46:49], v[134:137], v[174:177], v[46:49]
	v_mfma_f32_16x16x32_bf16 v[42:45], v[142:145], v[174:177], v[42:45]
	v_mfma_f32_16x16x32_bf16 v[30:33], v[134:137], v[182:185], v[30:33]
	v_mfma_f32_16x16x32_bf16 v[26:29], v[142:145], v[182:185], v[26:29]
	v_mfma_f32_16x16x32_bf16 v[14:17], v[134:137], v[208:211], v[14:17]
	v_mfma_f32_16x16x32_bf16 v[10:13], v[142:145], v[208:211], v[10:13]
	s_setprio 0
	s_setprio 1
	v_mfma_f32_16x16x32_bf16 v[54:57], v[146:149], v[162:165], 0
	v_mfma_f32_16x16x32_bf16 v[50:53], v[154:157], v[162:165], 0
	v_mfma_f32_16x16x32_bf16 v[38:41], v[146:149], v[170:173], 0
	v_mfma_f32_16x16x32_bf16 v[34:37], v[154:157], v[170:173], 0
	v_mfma_f32_16x16x32_bf16 v[22:25], v[146:149], v[178:181], 0
	v_mfma_f32_16x16x32_bf16 v[18:21], v[154:157], v[178:181], 0
	v_mfma_f32_16x16x32_bf16 v[6:9], v[146:149], v[204:207], 0
	v_mfma_f32_16x16x32_bf16 v[2:5], v[154:157], v[204:207], 0
	v_mfma_f32_16x16x32_bf16 v[54:57], v[150:153], v[166:169], v[54:57]
	v_mfma_f32_16x16x32_bf16 v[50:53], v[158:161], v[166:169], v[50:53]
	v_mfma_f32_16x16x32_bf16 v[38:41], v[150:153], v[174:177], v[38:41]
	v_mfma_f32_16x16x32_bf16 v[34:37], v[158:161], v[174:177], v[34:37]
	v_mfma_f32_16x16x32_bf16 v[22:25], v[150:153], v[182:185], v[22:25]
	v_mfma_f32_16x16x32_bf16 v[18:21], v[158:161], v[182:185], v[18:21]
	v_mfma_f32_16x16x32_bf16 v[6:9], v[150:153], v[208:211], v[6:9]
	v_mfma_f32_16x16x32_bf16 v[2:5], v[158:161], v[208:211], v[2:5]
	s_setprio 0
	s_barrier
	s_add_i32 s33, 0, 0x18000
	v_add_u32_e32 v0, s33, v245
	s_add_i32 s40, 0, 0x1c000
	ds_read_b128 v[130:133], v0
	ds_read_b128 v[134:137], v0 offset:1024
	ds_read_b128 v[138:141], v0 offset:2048
	ds_read_b128 v[142:145], v0 offset:3072
	v_add_u32_e32 v0, s40, v245
	ds_read_b128 v[146:149], v0
	ds_read_b128 v[150:153], v0 offset:1024
	ds_read_b128 v[154:157], v0 offset:2048
	ds_read_b128 v[158:161], v0 offset:3072
	s_add_u32 s48, s66, 0x40000
	s_addc_u32 s49, s67, 0
	s_mov_b32 m0, s42
	v_lshl_add_u64 v[216:217], s[48:49], 0, v[186:187]
	ds_read_b128 v[162:165], v246 offset:32768
	ds_read_b128 v[166:169], v246 offset:33792
	ds_read_b128 v[170:173], v246 offset:34816
	ds_read_b128 v[174:177], v246 offset:35840
	ds_read_b128 v[178:181], v246 offset:36864
	ds_read_b128 v[182:185], v246 offset:37888
	ds_read_b128 v[204:207], v246 offset:38912
	ds_read_b128 v[208:211], v246 offset:39936
	global_load_lds_dwordx4 v[216:217], off
	v_lshl_add_u64 v[216:217], s[48:49], 0, v[196:197]
	s_mov_b32 m0, s46
	s_nop 0
	global_load_lds_dwordx4 v[216:217], off
	s_waitcnt vmcnt(8)
	s_waitcnt lgkmcnt(0)
	s_barrier
	s_setprio 1
	s_waitcnt lgkmcnt(0)
	v_mfma_f32_16x16x32_bf16 v[126:129], v[130:133], v[162:165], v[126:129]
	v_mfma_f32_16x16x32_bf16 v[122:125], v[138:141], v[162:165], v[122:125]
	v_mfma_f32_16x16x32_bf16 v[110:113], v[130:133], v[170:173], v[110:113]
	v_mfma_f32_16x16x32_bf16 v[106:109], v[138:141], v[170:173], v[106:109]
	v_mfma_f32_16x16x32_bf16 v[94:97], v[130:133], v[178:181], v[94:97]
	v_mfma_f32_16x16x32_bf16 v[90:93], v[138:141], v[178:181], v[90:93]
	v_mfma_f32_16x16x32_bf16 v[78:81], v[130:133], v[204:207], v[78:81]
	v_mfma_f32_16x16x32_bf16 v[74:77], v[138:141], v[204:207], v[74:77]
	v_mfma_f32_16x16x32_bf16 v[126:129], v[134:137], v[166:169], v[126:129]
	v_mfma_f32_16x16x32_bf16 v[122:125], v[142:145], v[166:169], v[122:125]
	v_mfma_f32_16x16x32_bf16 v[110:113], v[134:137], v[174:177], v[110:113]
	v_mfma_f32_16x16x32_bf16 v[106:109], v[142:145], v[174:177], v[106:109]
	v_mfma_f32_16x16x32_bf16 v[94:97], v[134:137], v[182:185], v[94:97]
	v_mfma_f32_16x16x32_bf16 v[90:93], v[142:145], v[182:185], v[90:93]
	v_mfma_f32_16x16x32_bf16 v[78:81], v[134:137], v[208:211], v[78:81]
	v_mfma_f32_16x16x32_bf16 v[74:77], v[142:145], v[208:211], v[74:77]
	s_setprio 0
	s_setprio 1
	v_mfma_f32_16x16x32_bf16 v[118:121], v[146:149], v[162:165], v[118:121]
	v_mfma_f32_16x16x32_bf16 v[114:117], v[154:157], v[162:165], v[114:117]
	v_mfma_f32_16x16x32_bf16 v[102:105], v[146:149], v[170:173], v[102:105]
	v_mfma_f32_16x16x32_bf16 v[98:101], v[154:157], v[170:173], v[98:101]
	v_mfma_f32_16x16x32_bf16 v[86:89], v[146:149], v[178:181], v[86:89]
	v_mfma_f32_16x16x32_bf16 v[82:85], v[154:157], v[178:181], v[82:85]
	v_mfma_f32_16x16x32_bf16 v[70:73], v[146:149], v[204:207], v[70:73]
	v_mfma_f32_16x16x32_bf16 v[66:69], v[154:157], v[204:207], v[66:69]
	v_mfma_f32_16x16x32_bf16 v[118:121], v[150:153], v[166:169], v[118:121]
	v_mfma_f32_16x16x32_bf16 v[114:117], v[158:161], v[166:169], v[114:117]
	v_mfma_f32_16x16x32_bf16 v[102:105], v[150:153], v[174:177], v[102:105]
	v_mfma_f32_16x16x32_bf16 v[98:101], v[158:161], v[174:177], v[98:101]
	v_mfma_f32_16x16x32_bf16 v[86:89], v[150:153], v[182:185], v[86:89]
	v_mfma_f32_16x16x32_bf16 v[82:85], v[158:161], v[182:185], v[82:85]
	v_mfma_f32_16x16x32_bf16 v[70:73], v[150:153], v[208:211], v[70:73]
	v_mfma_f32_16x16x32_bf16 v[66:69], v[158:161], v[208:211], v[66:69]
	s_setprio 0
	s_barrier
	s_add_i32 s33, s33, s30
	v_lshl_add_u64 v[192:193], v[192:193], 0, s[86:87]
	s_mov_b32 m0, s33
	ds_read_b128 v[162:165], v246 offset:49152
	ds_read_b128 v[166:169], v246 offset:50176
	ds_read_b128 v[170:173], v246 offset:51200
	ds_read_b128 v[174:177], v246 offset:52224
	ds_read_b128 v[178:181], v246 offset:53248
	ds_read_b128 v[182:185], v246 offset:54272
	ds_read_b128 v[204:207], v246 offset:55296
	ds_read_b128 v[208:211], v246 offset:56320
	global_load_lds_dwordx4 v[192:193], off
	s_add_i32 m0, s33, 0x2000
	s_add_u32 s48, s58, 0x40080
	v_lshl_add_u64 v[192:193], v[194:195], 0, s[86:87]
	s_addc_u32 s49, s59, 0
	s_add_i32 s33, s40, s30
	global_load_lds_dwordx4 v[192:193], off
	v_lshl_add_u64 v[192:193], s[48:49], 0, v[188:189]
	s_mov_b32 m0, s33
	s_nop 0
	global_load_lds_dwordx4 v[192:193], off
	v_lshl_add_u64 v[192:193], s[48:49], 0, v[198:199]
	s_add_i32 m0, s33, 0x2000
	s_nop 0
	global_load_lds_dwordx4 v[192:193], off
	v_lshl_add_u64 v[192:193], v[212:213], 0, s[86:87]
	s_mov_b32 m0, s74
	s_nop 0
	global_load_lds_dwordx4 v[192:193], off
	v_lshl_add_u64 v[192:193], v[214:215], 0, s[86:87]
	s_mov_b32 m0, s76
	s_nop 0
	global_load_lds_dwordx4 v[192:193], off
	s_waitcnt vmcnt(8)
	s_waitcnt lgkmcnt(0)
	s_barrier
	s_setprio 1
	s_waitcnt lgkmcnt(0)
	v_mfma_f32_16x16x32_bf16 v[62:65], v[130:133], v[162:165], v[62:65]
	v_mfma_f32_16x16x32_bf16 v[58:61], v[138:141], v[162:165], v[58:61]
	v_mfma_f32_16x16x32_bf16 v[46:49], v[130:133], v[170:173], v[46:49]
	v_mfma_f32_16x16x32_bf16 v[42:45], v[138:141], v[170:173], v[42:45]
	v_mfma_f32_16x16x32_bf16 v[30:33], v[130:133], v[178:181], v[30:33]
	v_mfma_f32_16x16x32_bf16 v[26:29], v[138:141], v[178:181], v[26:29]
	v_mfma_f32_16x16x32_bf16 v[14:17], v[130:133], v[204:207], v[14:17]
	v_mfma_f32_16x16x32_bf16 v[10:13], v[138:141], v[204:207], v[10:13]
	v_mfma_f32_16x16x32_bf16 v[62:65], v[134:137], v[166:169], v[62:65]
	v_mfma_f32_16x16x32_bf16 v[58:61], v[142:145], v[166:169], v[58:61]
	v_mfma_f32_16x16x32_bf16 v[46:49], v[134:137], v[174:177], v[46:49]
	v_mfma_f32_16x16x32_bf16 v[42:45], v[142:145], v[174:177], v[42:45]
	v_mfma_f32_16x16x32_bf16 v[30:33], v[134:137], v[182:185], v[30:33]
	v_mfma_f32_16x16x32_bf16 v[26:29], v[142:145], v[182:185], v[26:29]
	v_mfma_f32_16x16x32_bf16 v[14:17], v[134:137], v[208:211], v[14:17]
	v_mfma_f32_16x16x32_bf16 v[10:13], v[142:145], v[208:211], v[10:13]
	s_setprio 0
	s_setprio 1
	v_mfma_f32_16x16x32_bf16 v[54:57], v[146:149], v[162:165], v[54:57]
	v_mfma_f32_16x16x32_bf16 v[50:53], v[154:157], v[162:165], v[50:53]
	v_mfma_f32_16x16x32_bf16 v[38:41], v[146:149], v[170:173], v[38:41]
	v_mfma_f32_16x16x32_bf16 v[34:37], v[154:157], v[170:173], v[34:37]
	v_mfma_f32_16x16x32_bf16 v[22:25], v[146:149], v[178:181], v[22:25]
	v_mfma_f32_16x16x32_bf16 v[18:21], v[154:157], v[178:181], v[18:21]
	v_mfma_f32_16x16x32_bf16 v[6:9], v[146:149], v[204:207], v[6:9]
	v_mfma_f32_16x16x32_bf16 v[2:5], v[154:157], v[204:207], v[2:5]
	v_mfma_f32_16x16x32_bf16 v[54:57], v[150:153], v[166:169], v[54:57]
	v_mfma_f32_16x16x32_bf16 v[50:53], v[158:161], v[166:169], v[50:53]
	v_mfma_f32_16x16x32_bf16 v[38:41], v[150:153], v[174:177], v[38:41]
	v_mfma_f32_16x16x32_bf16 v[34:37], v[158:161], v[174:177], v[34:37]
	v_mfma_f32_16x16x32_bf16 v[22:25], v[150:153], v[182:185], v[22:25]
	v_mfma_f32_16x16x32_bf16 v[18:21], v[158:161], v[182:185], v[18:21]
	v_mfma_f32_16x16x32_bf16 v[6:9], v[150:153], v[208:211], v[6:9]
	v_mfma_f32_16x16x32_bf16 v[2:5], v[158:161], v[208:211], v[2:5]
	s_setprio 0
	s_barrier
	s_add_i32 s29, s29, 2
	s_add_u32 s10, s10, 0x100
	s_addc_u32 s11, s11, 0
	s_add_u32 s15, s15, 0x100
	s_addc_u32 s27, s27, 0
	s_cmp_gt_u32 s29, 13
